# v27 plus attention epilogue and MLA last-tile packed f32 ops split into scalar ops
# baseline (speedup 1.0000x reference)
; DI float bflo(u32 w) { return __uint_as_float(w << 16); }
; DI float bfhi(u32 w) { return __uint_as_float(w & 0xffff0000u); }
; template <int DQK, bool ALIBI>
; DI void attn_pass(const u16* __restrict__ Qp, int ldq, const u16* __restrict__ Kp, int ldk, const u16* __restrict__ VTp,
;                   int seq_start, int kt_lo, int kt_hi, int q0, float slope2, f32x16 (&O)[4], float& lsum, char* lds) {
;     ...
;   lsum = l2.x + l2.y;
;   lsum += __shfl_xor(lsum, 32);
; DI void phase_attn_diff(int layer, float lam, float lam_init, float smax2, char* lds) {
;     ...
;       const float inv = 1.f / l;
;       if (map == 0) {
; #pragma unroll
;         for (int db = 0; db < 4; ++db)
; #pragma unroll
;           for (int g = 0; g < 4; ++g) {
;             uint2 o; o.x = pack2(O[db][4 * g] * inv, O[db][4 * g + 1] * inv); o.y = pack2(O[db][4 * g + 2] * inv, O[db][4 * g + 3] * inv);
;             *(uint2*)(ao + db * 32 + 8 * g + 4 * h) = o;
;           }
;       } else {
;         float ss = 0.f;
;         const float li = lam * inv;
; #pragma unroll
;         for (int db = 0; db < 4; ++db)
; #pragma unroll
;           for (int g = 0; g < 4; ++g) {
;             uint2 st = *(const uint2*)(ao + db * 32 + 8 * g + 4 * h);
;             float o0[4] = {bflo(st.x), bfhi(st.x), bflo(st.y), bfhi(st.y)};
; #pragma unroll
;             for (int e = 0; e < 4; ++e) {
;               float od = o0[e] - li * O[db][4 * g + e];
;               O[db][4 * g + e] = od;
;               ss += od * od;
;             }
;           }
;         ss += __shfl_xor(ss, 32);
;         const float rms = rsqrtf(ss * (1.f / 128.f) + EPSN) * (1.f - lam_init);
.LBB0_1163:
	v_cmp_lt_i32_e32 vcc, v215, v214
	v_add_f32_e32 v0, v142, v143
	s_nop 0
	v_cndmask_b32_e32 v66, v212, v215, vcc
	v_lshlrev_b32_e32 v108, 2, v66
	ds_bpermute_b32 v66, v108, v0
	s_waitcnt lgkmcnt(0)
	v_add_f32_e32 v0, v0, v66
	v_div_scale_f32 v66, s[6:7], v0, v0, 1.0
	v_rcp_f32_e32 v67, v66
	v_div_scale_f32 v68, vcc, 1.0, v0, 1.0
	s_mov_b64 s[6:7], -1
	v_fma_f32 v69, -v66, v67, 1.0
	v_fmac_f32_e32 v67, v69, v67
	v_mul_f32_e32 v69, v68, v67
	v_fma_f32 v70, -v66, v69, v68
	v_fmac_f32_e32 v69, v70, v67
	v_fma_f32 v66, -v66, v69, v68
	v_div_fmas_f32 v66, v66, v67, v69
	v_div_fixup_f32 v0, v66, v0, 1.0
	s_and_b64 vcc, exec, s[60:61]
	s_cbranch_vccz .LBB0_1165
	global_load_dwordx2 v[66:67], v[132:133], off
	global_load_dwordx2 v[68:69], v[132:133], off offset:16
	global_load_dwordx2 v[70:71], v[132:133], off offset:32
	global_load_dwordx2 v[72:73], v[132:133], off offset:48
	global_load_dwordx2 v[74:75], v[132:133], off offset:64
	global_load_dwordx2 v[76:77], v[132:133], off offset:80
	global_load_dwordx2 v[78:79], v[132:133], off offset:96
	global_load_dwordx2 v[80:81], v[132:133], off offset:112
	global_load_dwordx2 v[82:83], v[132:133], off offset:128
	global_load_dwordx2 v[84:85], v[132:133], off offset:144
	global_load_dwordx2 v[86:87], v[132:133], off offset:160
	global_load_dwordx2 v[88:89], v[132:133], off offset:176
	global_load_dwordx2 v[90:91], v[132:133], off offset:192
	global_load_dwordx2 v[92:93], v[132:133], off offset:208
	global_load_dwordx2 v[94:95], v[132:133], off offset:224
	global_load_dwordx2 v[96:97], v[132:133], off offset:240
	s_waitcnt vmcnt(18)
	v_mul_f32_e32 v114, v234, v0
	global_load_dwordx4 v[110:113], v[126:127], off
	s_waitcnt vmcnt(16)
	v_lshlrev_b32_e32 v98, 16, v66
	v_and_b32_e32 v99, 0xffff0000, v66
	v_lshlrev_b32_e32 v100, 16, v67
	v_and_b32_e32 v101, 0xffff0000, v67
	v_fma_f32 v170, -v50, v114, v98
	v_fma_f32 v171, -v51, v114, v99
	v_fma_f32 v166, -v52, v114, v100
	v_fma_f32 v167, -v53, v114, v101
	v_mul_f32_e32 v172, v170, v170
	v_mul_f32_e32 v173, v171, v171
	s_waitcnt vmcnt(15)
	v_lshlrev_b32_e32 v102, 16, v68
	v_and_b32_e32 v103, 0xffff0000, v68
	v_mul_f32_e32 v168, v166, v166
	v_mul_f32_e32 v169, v167, v167
	v_add_f32_e32 v109, v172, v173
	v_fma_f32 v178, -v54, v114, v102
	v_fma_f32 v179, -v55, v114, v103
	v_add_f32_e32 v109, v109, v168
	v_lshlrev_b32_e32 v104, 16, v69
	v_and_b32_e32 v105, 0xffff0000, v69
	v_mul_f32_e32 v180, v178, v178
	v_mul_f32_e32 v181, v179, v179
	v_add_f32_e32 v109, v169, v109
	v_fma_f32 v174, -v56, v114, v104
	v_fma_f32 v175, -v57, v114, v105
	v_add_f32_e32 v109, v180, v109
	s_waitcnt vmcnt(14)
	v_lshlrev_b32_e32 v106, 16, v70
	v_and_b32_e32 v107, 0xffff0000, v70
	v_mul_f32_e32 v176, v174, v174
	v_mul_f32_e32 v177, v175, v175
	v_add_f32_e32 v109, v181, v109
	v_fma_f32 v186, -v58, v114, v106
	v_fma_f32 v187, -v59, v114, v107
	v_add_f32_e32 v109, v176, v109
	v_lshlrev_b32_e32 v70, 16, v71
	v_and_b32_e32 v71, 0xffff0000, v71
	v_mul_f32_e32 v194, v186, v186
	v_mul_f32_e32 v195, v187, v187
	v_add_f32_e32 v109, v177, v109
	v_fma_f32 v182, -v60, v114, v70
	v_fma_f32 v183, -v61, v114, v71
	v_add_f32_e32 v109, v194, v109
	s_waitcnt vmcnt(13)
	v_lshlrev_b32_e32 v116, 16, v72
	v_and_b32_e32 v117, 0xffff0000, v72
	v_mul_f32_e32 v184, v182, v182
	v_mul_f32_e32 v185, v183, v183
	v_add_f32_e32 v109, v195, v109
	v_fma_f32 v116, -v62, v114, v116
	v_fma_f32 v117, -v63, v114, v117
	v_add_f32_e32 v109, v184, v109
	v_lshlrev_b32_e32 v72, 16, v73
	v_and_b32_e32 v73, 0xffff0000, v73
	v_mul_f32_e32 v200, v116, v116
	v_mul_f32_e32 v201, v117, v117
	v_add_f32_e32 v109, v185, v109
	v_fma_f32 v196, -v64, v114, v72
	v_fma_f32 v197, -v65, v114, v73
	v_add_f32_e32 v109, v200, v109
	s_waitcnt vmcnt(12)
	v_lshlrev_b32_e32 v118, 16, v74
	v_and_b32_e32 v119, 0xffff0000, v74
	v_mul_f32_e32 v198, v196, v196
	v_mul_f32_e32 v199, v197, v197
	v_add_f32_e32 v109, v201, v109
	v_fma_f32 v118, -v34, v114, v118
	v_fma_f32 v119, -v35, v114, v119
	v_add_f32_e32 v109, v198, v109
	v_lshlrev_b32_e32 v74, 16, v75
	v_and_b32_e32 v75, 0xffff0000, v75
	v_mul_f32_e32 v204, v118, v118
	v_mul_f32_e32 v205, v119, v119
	v_add_f32_e32 v109, v199, v109
	v_fma_f32 v104, -v36, v114, v74
	v_fma_f32 v105, -v37, v114, v75
	v_add_f32_e32 v109, v204, v109
	s_waitcnt vmcnt(11)
	v_lshlrev_b32_e32 v120, 16, v76
	v_and_b32_e32 v121, 0xffff0000, v76
	v_mul_f32_e32 v202, v104, v104
	v_mul_f32_e32 v203, v105, v105
	v_add_f32_e32 v109, v205, v109
	v_fma_f32 v120, -v38, v114, v120
	v_fma_f32 v121, -v39, v114, v121
	v_add_f32_e32 v109, v202, v109
	v_lshlrev_b32_e32 v76, 16, v77
	v_and_b32_e32 v77, 0xffff0000, v77
	v_mul_f32_e32 v238, v120, v120
	v_mul_f32_e32 v239, v121, v121
	v_add_f32_e32 v109, v203, v109
	v_fma_f32 v100, -v40, v114, v76
	v_fma_f32 v101, -v41, v114, v77
	v_add_f32_e32 v109, v238, v109
	s_waitcnt vmcnt(10)
	v_lshlrev_b32_e32 v122, 16, v78
	v_and_b32_e32 v123, 0xffff0000, v78
	v_mul_f32_e32 v236, v100, v100
	v_mul_f32_e32 v237, v101, v101
	v_add_f32_e32 v109, v239, v109
	v_fma_f32 v122, -v42, v114, v122
	v_fma_f32 v123, -v43, v114, v123
	v_add_f32_e32 v109, v236, v109
	v_lshlrev_b32_e32 v78, 16, v79
	v_and_b32_e32 v79, 0xffff0000, v79
	v_mul_f32_e32 v242, v122, v122
	v_mul_f32_e32 v243, v123, v123
	v_add_f32_e32 v109, v237, v109
	s_waitcnt vmcnt(1)
; DI float bflo(u32 w) { return __uint_as_float(w << 16); }
; DI float bfhi(u32 w) { return __uint_as_float(w & 0xffff0000u); }
; DI void phase_attn_diff(int layer, float lam, float lam_init, float smax2, char* lds) {
;     ...
;         float ss = 0.f;
;         const float li = lam * inv;
; #pragma unroll
;         for (int db = 0; db < 4; ++db)
; #pragma unroll
;           for (int g = 0; g < 4; ++g) {
;             uint2 st = *(const uint2*)(ao + db * 32 + 8 * g + 4 * h);
;             float o0[4] = {bflo(st.x), bfhi(st.x), bflo(st.y), bfhi(st.y)};
; #pragma unroll
;             for (int e = 0; e < 4; ++e) {
;               float od = o0[e] - li * O[db][4 * g + e];
;               O[db][4 * g + e] = od;
;               ss += od * od;
;             }
;           }
;         ss += __shfl_xor(ss, 32);
;         const float rms = rsqrtf(ss * (1.f / 128.f) + EPSN) * (1.f - lam_init);
	v_lshlrev_b32_e32 v66, 16, v96
	v_and_b32_e32 v67, 0xffff0000, v96
	v_lshlrev_b32_e32 v68, 16, v97
	v_and_b32_e32 v69, 0xffff0000, v97
	v_fma_f32 v96, -v44, v114, v78
	v_fma_f32 v97, -v45, v114, v79
	v_add_f32_e32 v109, v242, v109
	v_lshlrev_b32_e32 v124, 16, v80
	v_and_b32_e32 v125, 0xffff0000, v80
	v_mul_f32_e32 v240, v96, v96
	v_mul_f32_e32 v241, v97, v97
	v_add_f32_e32 v109, v243, v109
	v_fma_f32 v106, -v46, v114, v124
	v_fma_f32 v107, -v47, v114, v125
	v_add_f32_e32 v109, v240, v109
	v_lshlrev_b32_e32 v80, 16, v81
	v_and_b32_e32 v81, 0xffff0000, v81
	v_mul_f32_e32 v124, v106, v106
	v_mul_f32_e32 v125, v107, v107
	v_add_f32_e32 v109, v241, v109
	v_lshlrev_b32_e32 v154, 16, v92
	v_and_b32_e32 v155, 0xffff0000, v92
	v_lshlrev_b32_e32 v156, 16, v93
	v_and_b32_e32 v157, 0xffff0000, v93
	v_fma_f32 v92, -v48, v114, v80
	v_fma_f32 v93, -v49, v114, v81
	v_add_f32_e32 v109, v124, v109
	v_lshlrev_b32_e32 v136, 16, v82
	v_and_b32_e32 v137, 0xffff0000, v82
	v_mul_f32_e32 v244, v92, v92
	v_mul_f32_e32 v245, v93, v93
	v_add_f32_e32 v109, v125, v109
	v_fma_f32 v102, -v18, v114, v136
	v_fma_f32 v103, -v19, v114, v137
	v_add_f32_e32 v109, v244, v109
	v_lshlrev_b32_e32 v82, 16, v83
	v_and_b32_e32 v83, 0xffff0000, v83
	v_mul_f32_e32 v136, v102, v102
	v_mul_f32_e32 v137, v103, v103
	v_add_f32_e32 v109, v245, v109
	v_lshlrev_b32_e32 v142, 16, v88
	v_and_b32_e32 v143, 0xffff0000, v88
	v_lshlrev_b32_e32 v144, 16, v89
	v_and_b32_e32 v145, 0xffff0000, v89
	v_fma_f32 v88, -v20, v114, v82
	v_fma_f32 v89, -v21, v114, v83
	v_add_f32_e32 v109, v136, v109
	v_lshlrev_b32_e32 v138, 16, v84
	v_and_b32_e32 v139, 0xffff0000, v84
	v_mul_f32_e32 v246, v88, v88
	v_mul_f32_e32 v247, v89, v89
	v_add_f32_e32 v109, v137, v109
	v_fma_f32 v98, -v22, v114, v138
	v_fma_f32 v99, -v23, v114, v139
	v_add_f32_e32 v109, v246, v109
	v_lshlrev_b32_e32 v84, 16, v85
	v_and_b32_e32 v85, 0xffff0000, v85
	v_mul_f32_e32 v138, v98, v98
	v_mul_f32_e32 v139, v99, v99
	v_add_f32_e32 v109, v247, v109
	v_fma_f32 v84, -v24, v114, v84
	v_fma_f32 v85, -v25, v114, v85
	v_add_f32_e32 v109, v138, v109
	v_lshlrev_b32_e32 v140, 16, v86
	v_and_b32_e32 v141, 0xffff0000, v86
	v_mul_f32_e32 v248, v84, v84
	v_mul_f32_e32 v249, v85, v85
	v_add_f32_e32 v109, v139, v109
	v_lshlrev_b32_e32 v158, 16, v94
	v_and_b32_e32 v159, 0xffff0000, v94
	v_lshlrev_b32_e32 v160, 16, v95
	v_and_b32_e32 v161, 0xffff0000, v95
	v_fma_f32 v94, -v26, v114, v140
	v_fma_f32 v95, -v27, v114, v141
	v_add_f32_e32 v109, v248, v109
	v_lshlrev_b32_e32 v86, 16, v87
	v_and_b32_e32 v87, 0xffff0000, v87
	v_mul_f32_e32 v140, v94, v94
	v_mul_f32_e32 v141, v95, v95
	v_add_f32_e32 v109, v249, v109
	v_fma_f32 v80, -v28, v114, v86
	v_fma_f32 v81, -v29, v114, v87
	v_add_f32_e32 v109, v140, v109
	v_mul_f32_e32 v250, v80, v80
	v_mul_f32_e32 v251, v81, v81
	v_add_f32_e32 v109, v141, v109
	v_lshlrev_b32_e32 v150, 16, v90
	v_and_b32_e32 v151, 0xffff0000, v90
	v_lshlrev_b32_e32 v152, 16, v91
	v_and_b32_e32 v153, 0xffff0000, v91
	v_fma_f32 v90, -v30, v114, v142
	v_fma_f32 v91, -v31, v114, v143
	v_add_f32_e32 v109, v250, v109
	v_mul_f32_e32 v142, v90, v90
	v_mul_f32_e32 v143, v91, v91
	v_add_f32_e32 v109, v251, v109
	v_fma_f32 v76, -v32, v114, v144
	v_fma_f32 v77, -v33, v114, v145
	v_add_f32_e32 v109, v142, v109
	v_mul_f32_e32 v144, v76, v76
	v_mul_f32_e32 v145, v77, v77
	v_add_f32_e32 v109, v143, v109
	v_fma_f32 v86, -v2, v114, v150
	v_fma_f32 v87, -v3, v114, v151
	v_add_f32_e32 v109, v144, v109
	v_mul_f32_e32 v150, v86, v86
	v_mul_f32_e32 v151, v87, v87
	v_add_f32_e32 v109, v145, v109
	v_fma_f32 v74, -v4, v114, v152
	v_fma_f32 v75, -v5, v114, v153
	v_add_f32_e32 v109, v150, v109
	v_mul_f32_e32 v152, v74, v74
	v_mul_f32_e32 v153, v75, v75
	v_add_f32_e32 v109, v151, v109
	v_fma_f32 v82, -v6, v114, v154
	v_fma_f32 v83, -v7, v114, v155
	v_add_f32_e32 v109, v152, v109
	v_mul_f32_e32 v154, v82, v82
	v_mul_f32_e32 v155, v83, v83
	v_add_f32_e32 v109, v153, v109
	v_fma_f32 v72, -v8, v114, v156
	v_fma_f32 v73, -v9, v114, v157
	v_add_f32_e32 v109, v154, v109
	v_mul_f32_e32 v156, v72, v72
	v_mul_f32_e32 v157, v73, v73
	v_add_f32_e32 v109, v155, v109
	v_fma_f32 v78, -v10, v114, v158
	v_fma_f32 v79, -v11, v114, v159
	v_add_f32_e32 v109, v156, v109
	v_fma_f32 v66, -v14, v114, v66
	v_fma_f32 v67, -v15, v114, v67
	v_fma_f32 v68, -v16, v114, v68
	v_fma_f32 v69, -v17, v114, v69
	v_fma_f32 v70, -v12, v114, v160
	v_fma_f32 v71, -v13, v114, v161
	v_mul_f32_e32 v114, v78, v78
	v_mul_f32_e32 v115, v79, v79
	v_add_f32_e32 v109, v157, v109
	v_add_f32_e32 v109, v114, v109
	v_mul_f32_e32 v160, v70, v70
	v_mul_f32_e32 v161, v71, v71
	v_add_f32_e32 v109, v115, v109
	v_add_f32_e32 v109, v160, v109
	v_mul_f32_e32 v162, v66, v66
	v_mul_f32_e32 v163, v67, v67
	v_add_f32_e32 v109, v161, v109
	v_add_f32_e32 v109, v162, v109
	v_mul_f32_e32 v164, v68, v68
	v_mul_f32_e32 v165, v69, v69
	v_add_f32_e32 v109, v163, v109
	v_add_f32_e32 v109, v164, v109
	v_add_f32_e32 v109, v165, v109
	ds_bpermute_b32 v108, v108, v109
	s_waitcnt lgkmcnt(0)
	v_add_f32_e32 v108, v109, v108
	v_fmamk_f32 v108, v108, 0x3c000000, v190
	v_mul_f32_e32 v109, 0x4b800000, v108
	v_cmp_gt_f32_e32 vcc, s12, v108
	s_nop 1
	v_cndmask_b32_e32 v108, v108, v109, vcc
	v_rsq_f32_e32 v108, v108
	s_nop 0
	v_mul_f32_e32 v109, 0x45800000, v108
	v_cndmask_b32_e32 v108, v108, v109, vcc
	v_mul_f32_e32 v114, v148, v108
	v_mul_f32_e32 v108, v170, v114
	v_mul_f32_e32 v109, v171, v114
	v_mul_f32_e32 v124, v174, v114
	v_mul_f32_e32 v125, v175, v114
	s_waitcnt vmcnt(0)
; DI void phase_attn_diff(int layer, float lam, float lam_init, float smax2, char* lds) {
;     ...
; #pragma unroll
;         for (int db = 0; db < 4; ++db)
; #pragma unroll
;           for (int g = 0; g < 4; ++g) {
;             const int d0 = db * 32 + 8 * g + 4 * h;
;             float4 gg = *(const float4*)(subg + d0);
;             uint2 o; o.x = pack2(O[db][4 * g] * rms * gg.x, O[db][4 * g + 1] * rms * gg.y);
;             o.y = pack2(O[db][4 * g + 2] * rms * gg.z, O[db][4 * g + 3] * rms * gg.w);
;             *(uint2*)(ao + d0) = o;
;           }
	v_mul_f32_e32 v108, v110, v108
	v_mul_f32_e32 v109, v111, v109
	v_mul_f32_e32 v110, v166, v114
	v_mul_f32_e32 v111, v167, v114
	v_cvt_pk_bf16_f32 v108, v108, v109
	v_mul_f32_e32 v110, v112, v110
	v_mul_f32_e32 v111, v113, v111
	v_mul_f32_e32 v112, v178, v114
	v_mul_f32_e32 v113, v179, v114
	v_cvt_pk_bf16_f32 v109, v110, v111
	global_store_dwordx2 v[132:133], v[108:109], off
	global_load_dwordx4 v[108:111], v[126:127], off offset:32
	v_mul_f32_e32 v104, v104, v114
	v_mul_f32_e32 v105, v105, v114
	v_mul_f32_e32 v100, v100, v114
	v_mul_f32_e32 v101, v101, v114
	v_mul_f32_e32 v96, v96, v114
	v_mul_f32_e32 v97, v97, v114
	v_mul_f32_e32 v92, v92, v114
	v_mul_f32_e32 v93, v93, v114
	v_mul_f32_e32 v88, v88, v114
	v_mul_f32_e32 v89, v89, v114
	v_mul_f32_e32 v84, v84, v114
	v_mul_f32_e32 v85, v85, v114
	v_mul_f32_e32 v80, v80, v114
	v_mul_f32_e32 v81, v81, v114
	v_mul_f32_e32 v76, v76, v114
	v_mul_f32_e32 v77, v77, v114
	v_mul_f32_e32 v74, v74, v114
	v_mul_f32_e32 v75, v75, v114
	v_mul_f32_e32 v72, v72, v114
	v_mul_f32_e32 v73, v73, v114
	v_mul_f32_e32 v70, v70, v114
	v_mul_f32_e32 v71, v71, v114
	v_mul_f32_e32 v66, v66, v114
	v_mul_f32_e32 v67, v67, v114
	v_mul_f32_e32 v68, v68, v114
	v_mul_f32_e32 v69, v69, v114
	s_waitcnt vmcnt(0)
	v_mul_f32_e32 v108, v108, v112
	v_mul_f32_e32 v109, v109, v113
	v_mul_f32_e32 v110, v110, v124
	v_mul_f32_e32 v111, v111, v125
	v_cvt_pk_bf16_f32 v108, v108, v109
	v_cvt_pk_bf16_f32 v109, v110, v111
	global_store_dwordx2 v[132:133], v[108:109], off offset:16
	global_load_dwordx4 v[108:111], v[126:127], off offset:64
	v_mul_f32_e32 v112, v186, v114
	v_mul_f32_e32 v113, v187, v114
	v_mul_f32_e32 v124, v182, v114
	v_mul_f32_e32 v125, v183, v114
	s_waitcnt vmcnt(0)
	v_mul_f32_e32 v108, v108, v112
	v_mul_f32_e32 v109, v109, v113
	v_mul_f32_e32 v110, v110, v124
	v_mul_f32_e32 v111, v111, v125
	v_cvt_pk_bf16_f32 v108, v108, v109
	v_cvt_pk_bf16_f32 v109, v110, v111
	global_store_dwordx2 v[132:133], v[108:109], off offset:32
	global_load_dwordx4 v[108:111], v[126:127], off offset:96
	v_mul_f32_e32 v112, v116, v114
	v_mul_f32_e32 v113, v117, v114
	v_mul_f32_e32 v116, v196, v114
	v_mul_f32_e32 v117, v197, v114
	s_waitcnt vmcnt(0)
	v_mul_f32_e32 v108, v108, v112
	v_mul_f32_e32 v109, v109, v113
	v_mul_f32_e32 v110, v110, v116
	v_mul_f32_e32 v111, v111, v117
	v_cvt_pk_bf16_f32 v108, v108, v109
	v_cvt_pk_bf16_f32 v109, v110, v111
	global_store_dwordx2 v[132:133], v[108:109], off offset:48
	global_load_dwordx4 v[108:111], v[126:127], off offset:128
	v_mul_f32_e32 v112, v118, v114
	v_mul_f32_e32 v113, v119, v114
	s_waitcnt vmcnt(0)
	v_mul_f32_e32 v104, v110, v104
	v_mul_f32_e32 v105, v111, v105
	v_mul_f32_e32 v108, v108, v112
	v_mul_f32_e32 v109, v109, v113
	s_nop 0
	v_cvt_pk_bf16_f32 v108, v108, v109
	v_cvt_pk_bf16_f32 v109, v104, v105
	global_store_dwordx2 v[132:133], v[108:109], off offset:64
	global_load_dwordx4 v[108:111], v[126:127], off offset:160
	v_mul_f32_e32 v104, v120, v114
	v_mul_f32_e32 v105, v121, v114
	s_waitcnt vmcnt(0)
	v_mul_f32_e32 v100, v110, v100
	v_mul_f32_e32 v101, v111, v101
	v_mul_f32_e32 v104, v108, v104
	v_mul_f32_e32 v105, v109, v105
	s_nop 0
	v_cvt_pk_bf16_f32 v104, v104, v105
	v_cvt_pk_bf16_f32 v105, v100, v101
	global_store_dwordx2 v[132:133], v[104:105], off offset:80
	global_load_dwordx4 v[108:111], v[126:127], off offset:192
	v_mul_f32_e32 v100, v122, v114
	v_mul_f32_e32 v101, v123, v114
	s_waitcnt vmcnt(0)
; DI void phase_attn_diff(int layer, float lam, float lam_init, float smax2, char* lds) {
;     ...
; #pragma unroll
;         for (int db = 0; db < 4; ++db)
; #pragma unroll
;           for (int g = 0; g < 4; ++g) {
;             const int d0 = db * 32 + 8 * g + 4 * h;
;             float4 gg = *(const float4*)(subg + d0);
;             uint2 o; o.x = pack2(O[db][4 * g] * rms * gg.x, O[db][4 * g + 1] * rms * gg.y);
;             o.y = pack2(O[db][4 * g + 2] * rms * gg.z, O[db][4 * g + 3] * rms * gg.w);
;             *(uint2*)(ao + d0) = o;
;           }
	v_mul_f32_e32 v96, v110, v96
	v_mul_f32_e32 v97, v111, v97
	v_mul_f32_e32 v100, v108, v100
	v_mul_f32_e32 v101, v109, v101
	s_nop 0
	v_cvt_pk_bf16_f32 v100, v100, v101
	v_cvt_pk_bf16_f32 v101, v96, v97
	global_store_dwordx2 v[132:133], v[100:101], off offset:96
	global_load_dwordx4 v[108:111], v[126:127], off offset:224
	v_mul_f32_e32 v96, v106, v114
	v_mul_f32_e32 v97, v107, v114
	s_waitcnt vmcnt(0)
	v_mul_f32_e32 v92, v110, v92
	v_mul_f32_e32 v93, v111, v93
	v_mul_f32_e32 v96, v108, v96
	v_mul_f32_e32 v97, v109, v97
	s_nop 0
	v_cvt_pk_bf16_f32 v96, v96, v97
	v_cvt_pk_bf16_f32 v97, v92, v93
	global_store_dwordx2 v[132:133], v[96:97], off offset:112
	global_load_dwordx4 v[104:107], v[126:127], off offset:256
	v_mul_f32_e32 v92, v102, v114
	v_mul_f32_e32 v93, v103, v114
	s_waitcnt vmcnt(0)
	v_mul_f32_e32 v88, v88, v106
	v_mul_f32_e32 v89, v89, v107
	v_mul_f32_e32 v92, v92, v104
	v_mul_f32_e32 v93, v93, v105
	s_nop 0
	v_cvt_pk_bf16_f32 v92, v92, v93
	v_cvt_pk_bf16_f32 v93, v88, v89
	global_store_dwordx2 v[132:133], v[92:93], off offset:128
	global_load_dwordx4 v[100:103], v[126:127], off offset:288
	v_mul_f32_e32 v88, v98, v114
	v_mul_f32_e32 v89, v99, v114
	s_waitcnt vmcnt(0)
	v_mul_f32_e32 v84, v84, v102
	v_mul_f32_e32 v85, v85, v103
	v_mul_f32_e32 v88, v88, v100
	v_mul_f32_e32 v89, v89, v101
	s_nop 0
	v_cvt_pk_bf16_f32 v88, v88, v89
	v_cvt_pk_bf16_f32 v89, v84, v85
	global_store_dwordx2 v[132:133], v[88:89], off offset:144
	global_load_dwordx4 v[96:99], v[126:127], off offset:320
	v_mul_f32_e32 v84, v94, v114
	v_mul_f32_e32 v85, v95, v114
	s_waitcnt vmcnt(0)
	v_mul_f32_e32 v80, v80, v98
	v_mul_f32_e32 v81, v81, v99
	v_mul_f32_e32 v84, v84, v96
	v_mul_f32_e32 v85, v85, v97
	s_nop 0
	v_cvt_pk_bf16_f32 v84, v84, v85
	v_cvt_pk_bf16_f32 v85, v80, v81
	global_store_dwordx2 v[132:133], v[84:85], off offset:160
	global_load_dwordx4 v[92:95], v[126:127], off offset:352
	v_mul_f32_e32 v80, v90, v114
	v_mul_f32_e32 v81, v91, v114
	s_waitcnt vmcnt(0)
	v_mul_f32_e32 v76, v76, v94
	v_mul_f32_e32 v77, v77, v95
	v_mul_f32_e32 v80, v80, v92
	v_mul_f32_e32 v81, v81, v93
	s_nop 0
	v_cvt_pk_bf16_f32 v80, v80, v81
	v_cvt_pk_bf16_f32 v81, v76, v77
	global_store_dwordx2 v[132:133], v[80:81], off offset:176
	global_load_dwordx4 v[88:91], v[126:127], off offset:384
	v_mul_f32_e32 v76, v86, v114
	v_mul_f32_e32 v77, v87, v114
	v_mul_f32_e32 v80, v82, v114
	v_mul_f32_e32 v81, v83, v114
	s_waitcnt vmcnt(0)
	v_mul_f32_e32 v76, v76, v88
	v_mul_f32_e32 v77, v77, v89
	v_mul_f32_e32 v74, v74, v90
	v_mul_f32_e32 v75, v75, v91
	v_cvt_pk_bf16_f32 v76, v76, v77
	v_cvt_pk_bf16_f32 v77, v74, v75
	global_store_dwordx2 v[132:133], v[76:77], off offset:192
	global_load_dwordx4 v[74:77], v[126:127], off offset:416
	s_waitcnt vmcnt(0)
	v_mul_f32_e32 v74, v80, v74
	v_mul_f32_e32 v75, v81, v75
	v_mul_f32_e32 v72, v72, v76
	v_mul_f32_e32 v73, v73, v77
	v_cvt_pk_bf16_f32 v74, v74, v75
	v_cvt_pk_bf16_f32 v75, v72, v73
	global_store_dwordx2 v[132:133], v[74:75], off offset:208
	global_load_dwordx4 v[72:75], v[126:127], off offset:448
	v_mul_f32_e32 v76, v78, v114
	v_mul_f32_e32 v77, v79, v114
	s_waitcnt vmcnt(0)
	v_mul_f32_e32 v70, v70, v74
	v_mul_f32_e32 v71, v71, v75
	v_mul_f32_e32 v72, v76, v72
	v_mul_f32_e32 v73, v77, v73
	s_nop 0
	v_cvt_pk_bf16_f32 v72, v72, v73
	v_cvt_pk_bf16_f32 v73, v70, v71
	global_store_dwordx2 v[132:133], v[72:73], off offset:224
	global_load_dwordx4 v[70:73], v[126:127], off offset:480
	s_waitcnt vmcnt(0)
	v_mul_f32_e32 v66, v66, v70
	v_mul_f32_e32 v67, v67, v71
	v_mul_f32_e32 v68, v68, v72
	v_mul_f32_e32 v69, v69, v73
	v_cvt_pk_bf16_f32 v66, v66, v67
	v_cvt_pk_bf16_f32 v67, v68, v69
	global_store_dwordx2 v[132:133], v[66:67], off offset:240
	s_cbranch_execnz .LBB0_1138
	s_branch .LBB0_1166

; DI void phase_attn_diff(int layer, float lam, float lam_init, float smax2, char* lds) {
;     ...
;       if (map == 0) {
; #pragma unroll
;         for (int db = 0; db < 4; ++db)
; #pragma unroll
;           for (int g = 0; g < 4; ++g) {
;             uint2 o; o.x = pack2(O[db][4 * g] * inv, O[db][4 * g + 1] * inv); o.y = pack2(O[db][4 * g + 2] * inv, O[db][4 * g + 3] * inv);
;             *(uint2*)(ao + db * 32 + 8 * g + 4 * h) = o;
;           }
.LBB0_1166:
	v_mul_f32_e32 v50, v50, v0
	v_mul_f32_e32 v51, v51, v0
	v_mul_f32_e32 v52, v52, v0
	v_mul_f32_e32 v53, v53, v0
	v_mul_f32_e32 v34, v34, v0
	v_mul_f32_e32 v35, v35, v0
	v_mul_f32_e32 v36, v36, v0
	v_mul_f32_e32 v37, v37, v0
	v_mul_f32_e32 v18, v18, v0
	v_mul_f32_e32 v19, v19, v0
	v_mul_f32_e32 v20, v20, v0
	v_mul_f32_e32 v21, v21, v0
	v_mul_f32_e32 v2, v2, v0
	v_mul_f32_e32 v3, v3, v0
	v_mul_f32_e32 v4, v4, v0
	v_mul_f32_e32 v5, v5, v0
	v_cvt_pk_bf16_f32 v50, v50, v51
	v_cvt_pk_bf16_f32 v51, v52, v53
	v_cvt_pk_bf16_f32 v34, v34, v35
	v_cvt_pk_bf16_f32 v35, v36, v37
	v_cvt_pk_bf16_f32 v18, v18, v19
	v_cvt_pk_bf16_f32 v19, v20, v21
	v_cvt_pk_bf16_f32 v2, v2, v3
	v_cvt_pk_bf16_f32 v3, v4, v5
	global_store_dwordx2 v[132:133], v[50:51], off
	v_mul_f32_e32 v50, v54, v0
	v_mul_f32_e32 v51, v55, v0
	v_mul_f32_e32 v52, v56, v0
	v_mul_f32_e32 v53, v57, v0
	global_store_dwordx2 v[132:133], v[34:35], off offset:64
	v_mul_f32_e32 v34, v38, v0
	v_mul_f32_e32 v35, v39, v0
	v_mul_f32_e32 v36, v40, v0
	v_mul_f32_e32 v37, v41, v0
	global_store_dwordx2 v[132:133], v[18:19], off offset:128
	v_mul_f32_e32 v18, v22, v0
	v_mul_f32_e32 v19, v23, v0
	v_mul_f32_e32 v20, v24, v0
	v_mul_f32_e32 v21, v25, v0
	global_store_dwordx2 v[132:133], v[2:3], off offset:192
	v_mul_f32_e32 v2, v6, v0
	v_mul_f32_e32 v3, v7, v0
	v_mul_f32_e32 v4, v8, v0
	v_mul_f32_e32 v5, v9, v0
	v_cvt_pk_bf16_f32 v50, v50, v51
	v_cvt_pk_bf16_f32 v51, v52, v53
	v_cvt_pk_bf16_f32 v34, v34, v35
	v_cvt_pk_bf16_f32 v35, v36, v37
	v_cvt_pk_bf16_f32 v18, v18, v19
	v_cvt_pk_bf16_f32 v19, v20, v21
	v_cvt_pk_bf16_f32 v2, v2, v3
	v_cvt_pk_bf16_f32 v3, v4, v5
	global_store_dwordx2 v[132:133], v[50:51], off offset:16
	v_mul_f32_e32 v50, v58, v0
	v_mul_f32_e32 v51, v59, v0
	v_mul_f32_e32 v52, v60, v0
	v_mul_f32_e32 v53, v61, v0
	global_store_dwordx2 v[132:133], v[34:35], off offset:80
	v_mul_f32_e32 v34, v42, v0
	v_mul_f32_e32 v35, v43, v0
	v_mul_f32_e32 v36, v44, v0
	v_mul_f32_e32 v37, v45, v0
	global_store_dwordx2 v[132:133], v[18:19], off offset:144
	v_mul_f32_e32 v18, v26, v0
	v_mul_f32_e32 v19, v27, v0
	v_mul_f32_e32 v20, v28, v0
	v_mul_f32_e32 v21, v29, v0
	global_store_dwordx2 v[132:133], v[2:3], off offset:208
	v_mul_f32_e32 v2, v10, v0
	v_mul_f32_e32 v3, v11, v0
	v_mul_f32_e32 v4, v12, v0
	v_mul_f32_e32 v5, v13, v0
	v_cvt_pk_bf16_f32 v50, v50, v51
	v_cvt_pk_bf16_f32 v51, v52, v53
	v_cvt_pk_bf16_f32 v34, v34, v35
	v_cvt_pk_bf16_f32 v35, v36, v37
	v_cvt_pk_bf16_f32 v18, v18, v19
	v_cvt_pk_bf16_f32 v19, v20, v21
	v_cvt_pk_bf16_f32 v2, v2, v3
	v_cvt_pk_bf16_f32 v3, v4, v5
	global_store_dwordx2 v[132:133], v[50:51], off offset:32
	v_mul_f32_e32 v50, v62, v0
	v_mul_f32_e32 v51, v63, v0
	v_mul_f32_e32 v52, v64, v0
	v_mul_f32_e32 v53, v65, v0
	global_store_dwordx2 v[132:133], v[34:35], off offset:96
	v_mul_f32_e32 v34, v46, v0
	v_mul_f32_e32 v35, v47, v0
	v_mul_f32_e32 v36, v48, v0
	v_mul_f32_e32 v37, v49, v0
	global_store_dwordx2 v[132:133], v[18:19], off offset:160
	v_mul_f32_e32 v18, v30, v0
	v_mul_f32_e32 v19, v31, v0
	v_mul_f32_e32 v20, v32, v0
	v_mul_f32_e32 v21, v33, v0
	global_store_dwordx2 v[132:133], v[2:3], off offset:224
	v_mul_f32_e32 v2, v14, v0
	v_mul_f32_e32 v3, v15, v0
	v_mul_f32_e32 v4, v16, v0
	v_mul_f32_e32 v5, v17, v0
	v_cvt_pk_bf16_f32 v50, v50, v51
	v_cvt_pk_bf16_f32 v51, v52, v53
	v_cvt_pk_bf16_f32 v34, v34, v35
	v_cvt_pk_bf16_f32 v35, v36, v37
	v_cvt_pk_bf16_f32 v18, v18, v19
	v_cvt_pk_bf16_f32 v19, v20, v21
	v_cvt_pk_bf16_f32 v2, v2, v3
	v_cvt_pk_bf16_f32 v3, v4, v5
	global_store_dwordx2 v[132:133], v[50:51], off offset:48
	global_store_dwordx2 v[132:133], v[34:35], off offset:112
	global_store_dwordx2 v[132:133], v[18:19], off offset:176
	global_store_dwordx2 v[132:133], v[2:3], off offset:240
	s_branch .LBB0_1138

; #define MFMA(a, b, c) __builtin_amdgcn_mfma_f32_32x32x16_bf16((a), (b), (c), 0, 0, 0)
; template <int DQK, bool ALIBI>
; DI void attn_pass(const u16* __restrict__ Qp, int ldq, const u16* __restrict__ Kp, int ldk, const u16* __restrict__ VTp,
;                   int seq_start, int kt_lo, int kt_hi, int q0, float slope2, f32x16 (&O)[4], float& lsum, char* lds) {
;     ...
;       S0 = MFMA(k0[ks], qf[ks], S0);
;       S1 = MFMA(k1[ks], qf[ks], S1);
;     }
;     if (kt + 1 < kt_hi) ATT_LSTORE(cur ^ 1);
;     if (kt + 2 < kt_hi) ATT_GLOAD(kt + 2);
; #pragma unroll
;     for (int s = 0; s < 2; ++s)
; #pragma unroll
;       for (int db = 0; db < 4; ++db) vf[s][db] = *(const bf16x8*)(Vs + (db * 32 + r) * 72 + s * 16 + h * 8);
;     __builtin_amdgcn_sched_barrier(0);
;     bf16x8 pf[2];
;     ...
;     ATT_SOFTMAX(S0);
;     __builtin_amdgcn_sched_barrier(0);
; #pragma unroll
;     for (int s = 0; s < 2; ++s)
; #pragma unroll
;       for (int db = 0; db < 4; ++db) O[db] = MFMA(vf[s][db], pf[s], O[db]);
;     bf16x8 vg[2][4];
; #pragma unroll
;     for (int s = 0; s < 2; ++s)
; #pragma unroll
;       for (int db = 0; db < 4; ++db) vg[s][db] = *(const bf16x8*)(Vs + (db * 32 + r) * 72 + 32 + s * 16 + h * 8);
;     bf16x8 pg[2];
;     {
;       float pv[16];
; #pragma unroll
;       for (int i = 0; i < 16; ++i) pv[i] = __builtin_amdgcn_exp2f(S1[i]);
; #pragma unroll
;       for (int i = 0; i < 8; ++i) l2 += f32x2{pv[2 * i], pv[2 * i + 1]};
; #pragma unroll
;       for (int s = 0; s < 2; ++s) {
;         u32 a0 = pack2(pv[8 * s], pv[8 * s + 1]), a1 = pack2(pv[8 * s + 2], pv[8 * s + 3]);
;         u32 a2 = pack2(pv[8 * s + 4], pv[8 * s + 5]), a3 = pack2(pv[8 * s + 6], pv[8 * s + 7]);
;         u32x4 pk = {a0, a1, a2, a3};
;         pg[s] = __builtin_bit_cast(bf16x8, pk);
;       }
;     }
; #pragma unroll
;     for (int g = 0; g < 8; ++g) {
;       __builtin_amdgcn_sched_group_barrier(0x008, 1, 0);
;       __builtin_amdgcn_sched_group_barrier(0x100, 1, 0);
;       __builtin_amdgcn_sched_group_barrier(0x002, 5, 0);
;     }
;     __builtin_amdgcn_sched_barrier(0);
; #pragma unroll
;     for (int s = 0; s < 2; ++s)
; #pragma unroll
;       for (int db = 0; db < 4; ++db) O[db] = MFMA(vg[s][db], pg[s], O[db]);
.LBB0_1170:
	s_bitcmp1_b32 s49, 0
	s_cselect_b32 s42, 0x7c00, 0
	v_add3_u32 v74, s42, v154, v161
	ds_read_b128 v[66:69], v74
	s_waitcnt vmcnt(2)
	ds_read_b128 v[124:127], v74 offset:32
	ds_read_b128 v[70:73], v74 offset:6656
	s_waitcnt vmcnt(1)
	ds_read_b128 v[128:131], v74 offset:6688
	s_waitcnt vmcnt(0)
	ds_read_b128 v[132:135], v74 offset:64
	ds_read_b128 v[140:143], v74 offset:96
	ds_read_b128 v[144:147], v74 offset:6720
	ds_read_b128 v[152:155], v74 offset:6752
	ds_read_b128 v[156:159], v74 offset:128
	ds_read_b128 v[160:163], v74 offset:160
	ds_read_b128 v[164:167], v74 offset:6784
	ds_read_b128 v[168:171], v74 offset:6816
	v_add_u32_e32 v122, s67, v150
	s_waitcnt lgkmcnt(11)
	v_mfma_f32_32x32x16_bf16 v[82:97], v[66:69], v[118:121], 0
	s_waitcnt lgkmcnt(9)
	v_mfma_f32_32x32x16_bf16 v[66:81], v[70:73], v[118:121], 0
	v_mfma_f32_32x32x16_bf16 v[82:97], v[124:127], v[114:117], v[82:97]
	s_waitcnt lgkmcnt(8)
	v_mfma_f32_32x32x16_bf16 v[66:81], v[128:131], v[114:117], v[66:81]
	s_waitcnt lgkmcnt(7)
	v_mfma_f32_32x32x16_bf16 v[82:97], v[132:135], v[110:113], v[82:97]
	s_waitcnt lgkmcnt(5)
	v_mfma_f32_32x32x16_bf16 v[66:81], v[144:147], v[110:113], v[66:81]
	v_mfma_f32_32x32x16_bf16 v[82:97], v[140:143], v[106:109], v[82:97]
	s_waitcnt lgkmcnt(4)
	v_mfma_f32_32x32x16_bf16 v[66:81], v[152:155], v[106:109], v[66:81]
	s_waitcnt lgkmcnt(3)
	v_mfma_f32_32x32x16_bf16 v[82:97], v[156:159], v[102:105], v[82:97]
	s_waitcnt lgkmcnt(1)
	v_mfma_f32_32x32x16_bf16 v[66:81], v[164:167], v[102:105], v[66:81]
	v_or_b32_e32 v102, s42, v0
	v_add_u32_e32 v123, v102, v151
	ds_read_b128 v[102:105], v123 offset:13312
	ds_read_b128 v[106:109], v123 offset:13344
	ds_read_b128 v[110:113], v123 offset:17920
	ds_read_b128 v[114:117], v123 offset:17952
	ds_read_b128 v[118:121], v123 offset:22528
	ds_read_b128 v[124:127], v123 offset:22560
	ds_read_b128 v[128:131], v123 offset:27136
	ds_read_b128 v[132:135], v123 offset:27168
	v_mfma_f32_32x32x16_bf16 v[82:97], v[160:163], v[98:101], v[82:97]
	s_waitcnt lgkmcnt(8)
	v_mfma_f32_32x32x16_bf16 v[66:81], v[168:171], v[98:101], v[66:81]
	s_nop 9
	v_exp_f32_e32 v98, v82
	v_exp_f32_e32 v99, v83
	v_exp_f32_e32 v100, v84
	v_exp_f32_e32 v101, v85
	v_exp_f32_e32 v136, v86
	v_exp_f32_e32 v137, v87
	v_exp_f32_e32 v140, v88
	v_exp_f32_e32 v141, v89
	v_exp_f32_e32 v90, v90
	v_exp_f32_e32 v91, v91
	v_exp_f32_e32 v142, v96
	v_exp_f32_e32 v143, v97
	v_add_f32_e32 v96, v148, v98
	v_add_f32_e32 v97, v149, v99
	v_exp_f32_e32 v92, v92
	v_exp_f32_e32 v93, v93
	v_add_f32_e32 v96, v100, v96
	v_add_f32_e32 v97, v101, v97
	v_exp_f32_e32 v94, v94
	v_exp_f32_e32 v95, v95
	v_add_f32_e32 v96, v136, v96
	v_add_f32_e32 v97, v137, v97
	v_cvt_pk_bf16_f32 v86, v90, v91
	v_add_f32_e32 v96, v140, v96
	v_add_f32_e32 v97, v141, v97
	v_cvt_pk_bf16_f32 v82, v98, v99
	v_add_f32_e32 v90, v90, v96
	v_add_f32_e32 v91, v91, v97
	v_cvt_pk_bf16_f32 v83, v100, v101
	v_add_f32_e32 v90, v92, v90
	v_add_f32_e32 v91, v93, v91
	v_cvt_pk_bf16_f32 v84, v136, v137
	v_cvt_pk_bf16_f32 v85, v140, v141
	v_cvt_pk_bf16_f32 v87, v92, v93
	v_cvt_pk_bf16_f32 v88, v94, v95
	v_cvt_pk_bf16_f32 v89, v142, v143
	v_add_f32_e32 v136, v94, v90
	v_add_f32_e32 v137, v95, v91
	s_waitcnt lgkmcnt(7)
	v_mfma_f32_32x32x16_bf16 v[50:65], v[102:105], v[82:85], v[50:65]
	v_add3_u32 v0, s42, v151, v0
	v_exp_f32_e32 v74, v74
	v_exp_f32_e32 v75, v75
	v_exp_f32_e32 v76, v76
	v_exp_f32_e32 v77, v77
	v_exp_f32_e32 v78, v78
	v_exp_f32_e32 v79, v79
	s_waitcnt lgkmcnt(5)
	v_mfma_f32_32x32x16_bf16 v[34:49], v[110:113], v[82:85], v[34:49]
	ds_read_b128 v[110:113], v0 offset:27232
	ds_read_b128 v[90:93], v0 offset:27200
	v_exp_f32_e32 v80, v80
	v_exp_f32_e32 v81, v81
	s_waitcnt lgkmcnt(5)
	v_mfma_f32_32x32x16_bf16 v[18:33], v[118:121], v[82:85], v[18:33]
	ds_read_b128 v[94:97], v0 offset:13376
	v_exp_f32_e32 v118, v70
	v_exp_f32_e32 v119, v71
	v_exp_f32_e32 v120, v72
	v_exp_f32_e32 v121, v73
	v_cvt_pk_bf16_f32 v70, v74, v75
	v_cvt_pk_bf16_f32 v71, v76, v77
	v_cvt_pk_bf16_f32 v72, v78, v79
	v_cvt_pk_bf16_f32 v73, v80, v81
	s_waitcnt lgkmcnt(4)
	v_mfma_f32_32x32x16_bf16 v[2:17], v[128:131], v[82:85], v[2:17]
	ds_read_b128 v[82:85], v0 offset:17984
	v_mfma_f32_32x32x16_bf16 v[50:65], v[106:109], v[86:89], v[50:65]
	ds_read_b128 v[98:101], v0 offset:13408
	v_mfma_f32_32x32x16_bf16 v[34:49], v[114:117], v[86:89], v[34:49]
	v_exp_f32_e32 v114, v66
	v_exp_f32_e32 v115, v67
	v_exp_f32_e32 v116, v68
	v_exp_f32_e32 v117, v69
	ds_read_b128 v[102:105], v0 offset:18016
	v_cvt_pk_bf16_f32 v66, v114, v115
	v_cvt_pk_bf16_f32 v68, v118, v119
	v_cvt_pk_bf16_f32 v67, v116, v117
	v_cvt_pk_bf16_f32 v69, v120, v121
	v_mfma_f32_32x32x16_bf16 v[18:33], v[124:127], v[86:89], v[18:33]
	ds_read_b128 v[106:109], v0 offset:22624
	v_add_f32_e64 v124, v142, v136
	v_add_f32_e64 v125, v143, v137
	v_add_f32_e64 v114, v114, v124
	v_add_f32_e64 v115, v115, v125
	v_add_f32_e32 v114, v116, v114
	v_add_f32_e32 v115, v117, v115
	v_add_f32_e32 v114, v118, v114
	v_add_f32_e32 v115, v119, v115
	v_add_f32_e32 v114, v120, v114
	v_add_f32_e32 v115, v121, v115
	s_waitcnt lgkmcnt(7)
	v_mfma_f32_32x32x16_bf16 v[2:17], v[132:135], v[86:89], v[2:17]
	ds_read_b128 v[86:89], v0 offset:22592
	v_add_f32_e64 v74, v74, v114
	v_add_f32_e64 v75, v75, v115
	v_add_f32_e64 v74, v76, v74
	v_add_f32_e64 v75, v77, v75
	v_add_f32_e32 v74, v78, v74
	v_add_f32_e32 v75, v79, v75
	s_waitcnt lgkmcnt(5)
	v_mfma_f32_32x32x16_bf16 v[50:65], v[94:97], v[66:69], v[50:65]
	v_cmp_lt_i32_e32 vcc, v215, v214
	v_ashrrev_i32_e32 v123, 31, v122
	v_mov_b32_e32 v139, v1
	s_waitcnt lgkmcnt(0)
	s_barrier
; #define MFMA(a, b, c) __builtin_amdgcn_mfma_f32_32x32x16_bf16((a), (b), (c), 0, 0, 0)
; template <int DQK, bool ALIBI>
; DI void attn_pass(const u16* __restrict__ Qp, int ldq, const u16* __restrict__ Kp, int ldk, const u16* __restrict__ VTp,
;                   int seq_start, int kt_lo, int kt_hi, int q0, float slope2, f32x16 (&O)[4], float& lsum, char* lds) {
;     ...
;       for (int db = 0; db < 4; ++db) O[db] = MFMA(vg[s][db], pg[s], O[db]);
;     __syncthreads();
;   }
;   lsum = l2.x + l2.y;
;   lsum += __shfl_xor(lsum, 32);
; }
; DI void phase_attn_mla(char* lds) {
;     ...
;     const float inv = 1.f / l;
;     u16* ao = AO + (size_t)token * 1024 + 512 + head * 128;
; #pragma unroll
;     for (int db = 0; db < 4; ++db)
; #pragma unroll
;       for (int g = 0; g < 4; ++g) {
;         uint2 o; o.x = pack2(O[db][4 * g] * inv, O[db][4 * g + 1] * inv); o.y = pack2(O[db][4 * g + 2] * inv, O[db][4 * g + 3] * inv);
;         *(uint2*)(ao + db * 32 + 8 * g + 4 * h) = o;
;       }
	s_add_i32 s56, s56, s1
	v_mfma_f32_32x32x16_bf16 v[34:49], v[82:85], v[66:69], v[34:49]
	v_mfma_f32_32x32x16_bf16 v[18:33], v[86:89], v[66:69], v[18:33]
	v_mfma_f32_32x32x16_bf16 v[2:17], v[90:93], v[66:69], v[2:17]
	v_add_f32_e64 v66, v80, v74
	v_add_f32_e64 v67, v81, v75
	v_add_f32_e32 v0, v66, v67
	v_cndmask_b32_e32 v66, v212, v215, vcc
	v_lshlrev_b32_e32 v66, 2, v66
	ds_bpermute_b32 v66, v66, v0
	s_waitcnt lgkmcnt(0)
	v_add_f32_e32 v0, v0, v66
	v_div_scale_f32 v66, s[42:43], v0, v0, 1.0
	v_rcp_f32_e32 v67, v66
	v_mfma_f32_32x32x16_bf16 v[50:65], v[98:101], v[70:73], v[50:65]
	s_lshl_b32 s42, s65, 7
	s_ashr_i32 s43, s42, 31
	v_fma_f32 v68, -v66, v67, 1.0
	v_fmac_f32_e32 v67, v68, v67
	v_div_scale_f32 v68, vcc, 1.0, v0, 1.0
	v_mul_f32_e32 v69, v68, v67
	v_mfma_f32_32x32x16_bf16 v[34:49], v[102:105], v[70:73], v[34:49]
	s_cmpk_lt_i32 s56, 0xa0
	v_mfma_f32_32x32x16_bf16 v[18:33], v[106:109], v[70:73], v[18:33]
	v_mfma_f32_32x32x16_bf16 v[2:17], v[110:113], v[70:73], v[2:17]
	v_fma_f32 v70, -v66, v69, v68
	v_fmac_f32_e32 v69, v70, v67
	v_fma_f32 v66, -v66, v69, v68
	v_div_fmas_f32 v66, v66, v67, v69
	v_div_fixup_f32 v0, v66, v0, 1.0
	v_lshlrev_b64 v[66:67], 11, v[122:123]
	v_lshl_add_u64 v[66:67], s[6:7], 0, v[66:67]
	v_lshl_add_u64 v[66:67], s[42:43], 1, v[66:67]
	v_lshl_add_u64 v[66:67], v[66:67], 0, v[138:139]
	v_mul_f32_e32 v50, v50, v0
	v_mul_f32_e32 v51, v51, v0
	v_mul_f32_e32 v52, v52, v0
	v_mul_f32_e32 v53, v53, v0
	s_mov_b64 s[42:43], 0x9640400
	v_cvt_pk_bf16_f32 v50, v50, v51
	v_cvt_pk_bf16_f32 v51, v52, v53
	v_add_co_u32_e32 v52, vcc, s17, v66
	v_mul_f32_e32 v34, v34, v0
	v_mul_f32_e32 v35, v35, v0
	v_mul_f32_e32 v36, v36, v0
	v_mul_f32_e32 v37, v37, v0
	v_mul_f32_e32 v18, v18, v0
	v_mul_f32_e32 v19, v19, v0
	v_mul_f32_e32 v20, v20, v0
	v_mul_f32_e32 v21, v21, v0
	v_mul_f32_e32 v2, v2, v0
	v_mul_f32_e32 v3, v3, v0
	v_mul_f32_e32 v4, v4, v0
	v_mul_f32_e32 v5, v5, v0
	v_lshl_add_u64 v[68:69], v[66:67], 0, s[42:43]
	v_addc_co_u32_e32 v53, vcc, 0, v67, vcc
	v_cvt_pk_bf16_f32 v34, v34, v35
	v_cvt_pk_bf16_f32 v35, v36, v37
	v_cvt_pk_bf16_f32 v18, v18, v19
	v_cvt_pk_bf16_f32 v19, v20, v21
	v_cvt_pk_bf16_f32 v2, v2, v3
	v_cvt_pk_bf16_f32 v3, v4, v5
	global_store_dwordx2 v[52:53], v[50:51], off offset:1024
	v_mul_f32_e32 v50, v54, v0
	v_mul_f32_e32 v51, v55, v0
	v_mul_f32_e32 v52, v56, v0
	v_mul_f32_e32 v53, v57, v0
	global_store_dwordx2 v[68:69], v[34:35], off offset:64
	v_mul_f32_e32 v34, v38, v0
	v_mul_f32_e32 v35, v39, v0
	v_mul_f32_e32 v36, v40, v0
	v_mul_f32_e32 v37, v41, v0
	global_store_dwordx2 v[68:69], v[18:19], off offset:128
	v_mul_f32_e32 v18, v22, v0
	v_mul_f32_e32 v19, v23, v0
	v_mul_f32_e32 v20, v24, v0
	v_mul_f32_e32 v21, v25, v0
	global_store_dwordx2 v[68:69], v[2:3], off offset:192
	v_mul_f32_e32 v2, v6, v0
	v_mul_f32_e32 v3, v7, v0
	v_mul_f32_e32 v4, v8, v0
	v_mul_f32_e32 v5, v9, v0
	v_cvt_pk_bf16_f32 v50, v50, v51
	v_cvt_pk_bf16_f32 v51, v52, v53
	v_cvt_pk_bf16_f32 v34, v34, v35
	v_cvt_pk_bf16_f32 v35, v36, v37
	v_cvt_pk_bf16_f32 v18, v18, v19
	v_cvt_pk_bf16_f32 v19, v20, v21
	v_cvt_pk_bf16_f32 v2, v2, v3
	v_cvt_pk_bf16_f32 v3, v4, v5
	global_store_dwordx2 v[68:69], v[50:51], off offset:16
	v_mul_f32_e32 v50, v58, v0
	v_mul_f32_e32 v51, v59, v0
	v_mul_f32_e32 v52, v60, v0
	v_mul_f32_e32 v53, v61, v0
	global_store_dwordx2 v[68:69], v[34:35], off offset:80
	v_mul_f32_e32 v34, v42, v0
	v_mul_f32_e32 v35, v43, v0
	v_mul_f32_e32 v36, v44, v0
	v_mul_f32_e32 v37, v45, v0
	global_store_dwordx2 v[68:69], v[18:19], off offset:144
	v_mul_f32_e32 v18, v26, v0
	v_mul_f32_e32 v19, v27, v0
	v_mul_f32_e32 v20, v28, v0
	v_mul_f32_e32 v21, v29, v0
	global_store_dwordx2 v[68:69], v[2:3], off offset:208
	v_mul_f32_e32 v2, v10, v0
	v_mul_f32_e32 v3, v11, v0
	v_mul_f32_e32 v4, v12, v0
	v_mul_f32_e32 v5, v13, v0
	v_cvt_pk_bf16_f32 v50, v50, v51
	v_cvt_pk_bf16_f32 v51, v52, v53
	v_cvt_pk_bf16_f32 v34, v34, v35
	v_cvt_pk_bf16_f32 v35, v36, v37
	v_cvt_pk_bf16_f32 v18, v18, v19
	v_cvt_pk_bf16_f32 v19, v20, v21
	v_cvt_pk_bf16_f32 v2, v2, v3
	v_cvt_pk_bf16_f32 v3, v4, v5
	global_store_dwordx2 v[68:69], v[50:51], off offset:32
	v_mul_f32_e32 v50, v62, v0
	v_mul_f32_e32 v51, v63, v0
	v_mul_f32_e32 v52, v64, v0
	v_mul_f32_e32 v53, v65, v0
	global_store_dwordx2 v[68:69], v[34:35], off offset:96
	v_mul_f32_e32 v34, v46, v0
	v_mul_f32_e32 v35, v47, v0
	v_mul_f32_e32 v36, v48, v0
	v_mul_f32_e32 v37, v49, v0
	global_store_dwordx2 v[68:69], v[18:19], off offset:160
	v_mul_f32_e32 v18, v30, v0
	v_mul_f32_e32 v19, v31, v0
	v_mul_f32_e32 v20, v32, v0
	v_mul_f32_e32 v21, v33, v0
	global_store_dwordx2 v[68:69], v[2:3], off offset:224
	v_mul_f32_e32 v2, v14, v0
	v_mul_f32_e32 v3, v15, v0
	v_mul_f32_e32 v4, v16, v0
	v_mul_f32_e32 v5, v17, v0
	v_cvt_pk_bf16_f32 v50, v50, v51
	v_cvt_pk_bf16_f32 v51, v52, v53
	v_cvt_pk_bf16_f32 v34, v34, v35
	v_cvt_pk_bf16_f32 v35, v36, v37
	v_cvt_pk_bf16_f32 v18, v18, v19
	v_cvt_pk_bf16_f32 v19, v20, v21
	v_cvt_pk_bf16_f32 v2, v2, v3
	v_cvt_pk_bf16_f32 v3, v4, v5
	global_store_dwordx2 v[68:69], v[50:51], off offset:48
	global_store_dwordx2 v[68:69], v[34:35], off offset:112
	global_store_dwordx2 v[68:69], v[18:19], off offset:176
	global_store_dwordx2 v[68:69], v[2:3], off offset:240
	s_cbranch_scc0 .LBB0_1202
